# attention q-tile prep: row sum of squares as two interleaved v_pk_fma_f32 chains over the 16 value pairs (was ~45 scalar adds/fmacs after packed squares)
# baseline (speedup 1.0000x reference)
.Lattn_prio_skip:
	ds_read_b128 v[20:23], v243 offset:144
	ds_read_b128 v[16:19], v243 offset:16
	v_or_b32_e32 v153, s68, v184
	v_or_b32_e32 v98, s91, v153
	v_lshlrev_b32_e32 v96, 5, v98
	v_or_b32_e32 v24, v96, v126
	v_lshlrev_b32_e32 v54, 2, v24
	ds_read_b128 v[42:45], v243 offset:128
	ds_read_b128 v[24:27], v252 offset:4096
	ds_read_b128 v[28:31], v252 offset:22144
	ds_read_b128 v[46:49], v243
	ds_read_b128 v[50:53], v252
	s_nop 0
	ds_read_b128 v[54:57], v252 offset:16384
	s_lshl_b32 s55, s97, 2
	v_lshlrev_b32_e32 v34, 16, v15
	v_and_b32_e32 v32, 0xffff0000, v15
	v_lshlrev_b32_e32 v39, 16, v9
	v_and_b32_e32 v15, 0xffff0000, v9
	v_lshlrev_b32_e32 v41, 16, v8
	v_lshlrev_b32_e32 v40, 16, v12
	v_and_b32_e32 v9, 0xffff0000, v8
	v_and_b32_e32 v8, 0xffff0000, v12
	v_lshlrev_b32_e32 v12, 16, v7
	v_and_b32_e32 v58, 0xffff0000, v7
	v_lshlrev_b32_e32 v7, 16, v1
	v_and_b32_e32 v63, 0xffff0000, v1
	v_lshlrev_b32_e32 v65, 16, v0
	v_lshlrev_b32_e32 v64, 16, v4
	v_and_b32_e32 v1, 0xffff0000, v0
	v_and_b32_e32 v0, 0xffff0000, v4
	v_lshlrev_b32_e32 v35, 16, v11
	v_and_b32_e32 v33, 0xffff0000, v11
	v_lshlrev_b32_e32 v36, 16, v14
	v_lshlrev_b32_e32 v37, 16, v10
	v_and_b32_e32 v11, 0xffff0000, v10
	v_and_b32_e32 v10, 0xffff0000, v14
	v_lshlrev_b32_e32 v38, 16, v13
	v_and_b32_e32 v14, 0xffff0000, v13
	v_lshlrev_b32_e32 v13, 16, v3
	v_and_b32_e32 v59, 0xffff0000, v3
	v_lshlrev_b32_e32 v61, 16, v2
	v_lshlrev_b32_e32 v60, 16, v6
	v_and_b32_e32 v3, 0xffff0000, v2
	v_and_b32_e32 v2, 0xffff0000, v6
	v_lshlrev_b32_e32 v6, 16, v5
	v_mov_b32_e32 v99, s55
	v_and_b32_e32 v62, 0xffff0000, v5
	v_mov_b32_e32 v214, v253
	s_waitcnt lgkmcnt(0)
	v_mov_b32_e32 v162, v20
	s_waitcnt lgkmcnt(0)
	v_mov_b32_e32 v163, v16
	v_mov_b32_e32 v161, v18
	v_pk_mul_f32 v[236:237], v[0:1], v[0:1]
	v_pk_mul_f32 v[238:239], v[2:3], v[2:3]
	v_pk_fma_f32 v[236:237], v[6:7], v[6:7], v[236:237]
	v_pk_fma_f32 v[238:239], v[8:9], v[8:9], v[238:239]
	v_pk_fma_f32 v[236:237], v[10:11], v[10:11], v[236:237]
	v_pk_fma_f32 v[238:239], v[12:13], v[12:13], v[238:239]
	v_pk_fma_f32 v[236:237], v[14:15], v[14:15], v[236:237]
	v_pk_fma_f32 v[238:239], v[32:33], v[32:33], v[238:239]
	v_pk_fma_f32 v[236:237], v[34:35], v[34:35], v[236:237]
	v_pk_fma_f32 v[238:239], v[36:37], v[36:37], v[238:239]
	v_pk_fma_f32 v[236:237], v[38:39], v[38:39], v[236:237]
	v_pk_fma_f32 v[238:239], v[40:41], v[40:41], v[238:239]
	v_pk_fma_f32 v[236:237], v[58:59], v[58:59], v[236:237]
	v_pk_fma_f32 v[238:239], v[60:61], v[60:61], v[238:239]
	v_pk_fma_f32 v[236:237], v[62:63], v[62:63], v[236:237]
	v_pk_fma_f32 v[238:239], v[64:65], v[64:65], v[238:239]
	v_pk_add_f32 v[236:237], v[236:237], v[238:239]
	v_add_f32_e32 v16, v236, v237
	ds_bpermute_b32 v18, v188, v16
	s_waitcnt lgkmcnt(0)
	v_mov_b32_e32 v66, v42
	s_waitcnt lgkmcnt(0)
	v_mov_b32_e32 v67, v46
	v_mov_b32_e32 v46, v43
	v_mov_b32_e32 v68, v50
	s_waitcnt lgkmcnt(0)
	v_add_f32_e32 v16, v16, v18
	v_fmamk_f32 v16, v16, 0x3c800000, v189
	v_rsq_f32_e32 v16, v16
	v_mov_b32_e32 v69, v54
	v_mov_b32_e32 v164, v44
	v_mov_b32_e32 v165, v48
	v_mul_f32_e32 v70, 0x3e38aa3b, v16
	v_pk_mul_f32 v[64:65], v[70:71], v[64:65] op_sel_hi:[0,1]
	v_pk_mul_f32 v[0:1], v[70:71], v[0:1] op_sel_hi:[0,1]
	v_pk_mul_f32 v[64:65], v[66:67], v[64:65]
	v_mov_b32_e32 v66, v54
	v_mov_b32_e32 v67, v50
	v_pk_mul_f32 v[0:1], v[46:47], v[0:1]
	v_mov_b32_e32 v50, v55
	v_mov_b32_e32 v54, v51
	v_pk_mul_f32 v[42:43], v[50:51], v[0:1]
	v_pk_mul_f32 v[0:1], v[54:55], v[0:1]
	v_sub_f32_e32 v42, v43, v42
	v_add_f32_e32 v43, v0, v1
	v_pk_mul_f32 v[0:1], v[70:71], v[6:7] op_sel_hi:[0,1]
	v_mov_b32_e32 v4, v52
	v_mov_b32_e32 v5, v56
	v_pk_mul_f32 v[0:1], v[0:1], v[164:165]
	v_mov_b32_e32 v6, v56
	v_mov_b32_e32 v7, v52
	v_pk_mul_f32 v[6:7], v[0:1], v[6:7]
	v_pk_mul_f32 v[0:1], v[0:1], v[4:5]
	v_sub_f32_e32 v6, v7, v6
	v_add_f32_e32 v7, v0, v1
	v_pk_mul_f32 v[0:1], v[70:71], v[62:63] op_sel_hi:[0,1]
	v_mov_b32_e32 v48, v45
	v_pk_mul_f32 v[0:1], v[0:1], v[48:49]
	v_mov_b32_e32 v52, v57
	v_mov_b32_e32 v56, v53
	v_pk_mul_f32 v[4:5], v[0:1], v[52:53]
	v_pk_mul_f32 v[0:1], v[0:1], v[56:57]
	v_mov_b32_e32 v168, v24
	v_add_f32_e32 v45, v0, v1
	v_pk_mul_f32 v[0:1], v[70:71], v[60:61] op_sel_hi:[0,1]
	v_mov_b32_e32 v169, v28
	v_sub_f32_e32 v44, v5, v4
	v_pk_mul_f32 v[0:1], v[0:1], v[162:163]
	v_mov_b32_e32 v4, v28
	v_mov_b32_e32 v5, v24
	v_pk_mul_f32 v[4:5], v[0:1], v[4:5]
	v_pk_mul_f32 v[0:1], v[0:1], v[168:169]
	v_sub_f32_e32 v4, v5, v4
	v_add_f32_e32 v5, v0, v1
	v_pk_mul_f32 v[0:1], v[70:71], v[2:3] op_sel_hi:[0,1]
	v_mov_b32_e32 v16, v21
	v_pk_mul_f32 v[0:1], v[0:1], v[16:17]
	v_mov_b32_e32 v24, v29
	v_mov_b32_e32 v28, v25
	v_pk_mul_f32 v[2:3], v[0:1], v[24:25]
	v_pk_mul_f32 v[0:1], v[0:1], v[28:29]
	v_mov_b32_e32 v160, v22
	v_add_f32_e32 v17, v0, v1
	v_pk_mul_f32 v[0:1], v[70:71], v[12:13] op_sel_hi:[0,1]
	v_mov_b32_e32 v166, v26
	v_mov_b32_e32 v167, v30
	v_sub_f32_e32 v16, v3, v2
	v_pk_mul_f32 v[0:1], v[0:1], v[160:161]
	v_mov_b32_e32 v2, v30
	v_mov_b32_e32 v3, v26
	v_pk_mul_f32 v[2:3], v[0:1], v[2:3]
	v_pk_mul_f32 v[0:1], v[0:1], v[166:167]
	v_mov_b32_e32 v18, v23
	v_add_f32_e32 v13, v0, v1
	v_pk_mul_f32 v[0:1], v[70:71], v[58:59] op_sel_hi:[0,1]
	v_pk_mul_f32 v[0:1], v[0:1], v[18:19]
	v_mov_b32_e32 v26, v31
	v_mov_b32_e32 v30, v27
	v_sub_f32_e32 v12, v3, v2
	v_pk_mul_f32 v[2:3], v[0:1], v[26:27]
	v_pk_mul_f32 v[0:1], v[0:1], v[30:31]
	v_pk_mul_f32 v[66:67], v[66:67], v[64:65]
	v_pk_mul_f32 v[64:65], v[68:69], v[64:65]
	v_sub_f32_e32 v2, v3, v2
	v_add_f32_e32 v0, v0, v1
	v_sub_f32_e32 v20, v67, v66
	v_add_f32_e32 v22, v64, v65
	v_cvt_pk_bf16_f32 v48, v20, v42
	v_cvt_pk_bf16_f32 v49, v6, v44
	v_cvt_pk_bf16_f32 v50, v4, v16
	v_cvt_pk_bf16_f32 v51, v12, v2
	v_cvt_pk_bf16_f32 v116, v22, v43
	v_cvt_pk_bf16_f32 v117, v7, v45
	v_cvt_pk_bf16_f32 v118, v5, v17
	v_cvt_pk_bf16_f32 v119, v13, v0
	ds_read_b128 v[0:3], v243 offset:192
	ds_read_b128 v[4:7], v243 offset:64
	v_or_b32_e32 v96, v96, v127
	v_lshlrev_b32_e32 v12, 2, v96
	ds_read_b128 v[16:19], v252 offset:26240
	ds_read_b128 v[20:23], v252 offset:8192
	ds_read_b128 v[24:27], v243 offset:208
	ds_read_b128 v[28:31], v243 offset:80
	ds_read_b128 v[42:45], v252 offset:30336
	ds_read_b128 v[52:55], v252 offset:12288
	v_pk_mul_f32 v[12:13], v[70:71], v[40:41] op_sel_hi:[0,1]
	v_pk_mul_f32 v[8:9], v[70:71], v[8:9] op_sel_hi:[0,1]
	s_lshl_b32 s69, s97, 6
	s_cmp_eq_u32 s88, 0
	s_cselect_b64 s[78:79], -1, 0
	s_cmp_lg_u32 s88, 0
	s_waitcnt lgkmcnt(0)
	v_mov_b32_e32 v40, v0
	s_waitcnt lgkmcnt(0)
	v_mov_b32_e32 v41, v4
	v_pk_mul_f32 v[12:13], v[12:13], v[40:41]
	v_mov_b32_e32 v40, v16
	v_mov_b32_e32 v41, v20
	v_pk_mul_f32 v[40:41], v[12:13], v[40:41]
	v_mov_b32_e32 v4, v1
	v_sub_f32_e32 v46, v41, v40
	v_mov_b32_e32 v40, v20
	v_mov_b32_e32 v41, v16
	v_pk_mul_f32 v[0:1], v[8:9], v[4:5]
	v_mov_b32_e32 v20, v17
	v_mov_b32_e32 v16, v21
	v_pk_mul_f32 v[4:5], v[0:1], v[20:21]
	v_pk_mul_f32 v[0:1], v[0:1], v[16:17]
	v_sub_f32_e32 v8, v5, v4
	v_add_f32_e32 v9, v0, v1
	v_pk_mul_f32 v[0:1], v[70:71], v[38:39] op_sel_hi:[0,1]
	v_mov_b32_e32 v4, v2
	v_mov_b32_e32 v5, v6
	v_pk_mul_f32 v[0:1], v[0:1], v[4:5]
	v_mov_b32_e32 v4, v18
	v_mov_b32_e32 v5, v22
	v_pk_mul_f32 v[12:13], v[12:13], v[40:41]
	v_pk_mul_f32 v[4:5], v[0:1], v[4:5]
	v_add_f32_e32 v12, v12, v13
	v_sub_f32_e32 v13, v5, v4
	v_mov_b32_e32 v4, v22
	v_mov_b32_e32 v5, v18
	v_pk_mul_f32 v[0:1], v[0:1], v[4:5]
	v_mov_b32_e32 v6, v3
	v_add_f32_e32 v4, v0, v1
	v_pk_mul_f32 v[0:1], v[70:71], v[14:15] op_sel_hi:[0,1]
	v_pk_mul_f32 v[0:1], v[0:1], v[6:7]
	v_mov_b32_e32 v22, v19
	v_mov_b32_e32 v18, v23
	v_pk_mul_f32 v[2:3], v[0:1], v[22:23]
	v_pk_mul_f32 v[0:1], v[0:1], v[18:19]
	v_sub_f32_e32 v5, v3, v2
	v_add_f32_e32 v6, v0, v1
	v_pk_mul_f32 v[0:1], v[70:71], v[36:37] op_sel_hi:[0,1]
	s_waitcnt lgkmcnt(0)
	v_mov_b32_e32 v2, v24
	s_waitcnt lgkmcnt(0)
	v_mov_b32_e32 v3, v28
	v_pk_mul_f32 v[0:1], v[0:1], v[2:3]
	v_mov_b32_e32 v2, v42
	v_mov_b32_e32 v3, v52
	v_pk_mul_f32 v[2:3], v[0:1], v[2:3]
	v_mov_b32_e32 v28, v25
	v_sub_f32_e32 v7, v3, v2
	v_mov_b32_e32 v2, v52
	v_mov_b32_e32 v3, v42
	v_pk_mul_f32 v[0:1], v[0:1], v[2:3]
	v_mov_b32_e32 v52, v43
	v_add_f32_e32 v14, v0, v1
	v_pk_mul_f32 v[0:1], v[70:71], v[10:11] op_sel_hi:[0,1]
	v_pk_mul_f32 v[0:1], v[0:1], v[28:29]
	v_mov_b32_e32 v42, v53
	v_pk_mul_f32 v[2:3], v[0:1], v[52:53]
	v_pk_mul_f32 v[0:1], v[0:1], v[42:43]
	v_sub_f32_e32 v10, v3, v2
	v_add_f32_e32 v11, v0, v1
	v_pk_mul_f32 v[0:1], v[70:71], v[34:35] op_sel_hi:[0,1]
	v_mov_b32_e32 v2, v26
	v_mov_b32_e32 v3, v30
	v_pk_mul_f32 v[0:1], v[0:1], v[2:3]
	v_mov_b32_e32 v2, v44
	v_mov_b32_e32 v3, v54
	v_pk_mul_f32 v[2:3], v[0:1], v[2:3]
	v_mov_b32_e32 v30, v27
	v_sub_f32_e32 v15, v3, v2
	v_mov_b32_e32 v2, v54
	v_mov_b32_e32 v3, v44
	v_pk_mul_f32 v[0:1], v[0:1], v[2:3]
	v_mov_b32_e32 v54, v45
	v_add_f32_e32 v16, v0, v1
	v_pk_mul_f32 v[0:1], v[70:71], v[32:33] op_sel_hi:[0,1]
	v_pk_mul_f32 v[0:1], v[0:1], v[30:31]
	v_mov_b32_e32 v44, v55
	v_pk_mul_f32 v[2:3], v[0:1], v[54:55]
	v_pk_mul_f32 v[0:1], v[0:1], v[44:45]
	v_sub_f32_e32 v2, v3, v2
	v_add_f32_e32 v0, v0, v1
	v_cvt_pk_bf16_f32 v154, v46, v8
	v_cvt_pk_bf16_f32 v155, v13, v5
	v_cvt_pk_bf16_f32 v156, v7, v10
	v_cvt_pk_bf16_f32 v157, v15, v2
	v_cvt_pk_bf16_f32 v158, v12, v9
	v_cvt_pk_bf16_f32 v159, v4, v6
	v_cvt_pk_bf16_f32 v160, v14, v11
	v_cvt_pk_bf16_f32 v161, v16, v0
	s_barrier
	ds_read_b128 v[0:3], v192
	ds_read_b128 v[52:55], v195 offset:32
	s_waitcnt lgkmcnt(1)
	v_mfma_f32_32x32x16_bf16 v[64:79], v[0:3], v[48:51], 0
	ds_read_b128 v[0:3], v192 offset:32
	ds_read_b128 v[162:165], v196 offset:32
	s_waitcnt lgkmcnt(1)
	v_mfma_f32_32x32x16_bf16 v[64:79], v[0:3], v[154:157], v[64:79]
	ds_read_b128 v[0:3], v192 offset:64
	s_waitcnt lgkmcnt(0)
	v_mfma_f32_32x32x16_bf16 v[64:79], v[0:3], v[116:119], v[64:79]
	ds_read_b128 v[0:3], v192 offset:96
	s_waitcnt lgkmcnt(0)
	v_mfma_f32_32x32x16_bf16 v[64:79], v[0:3], v[158:161], v[64:79]
	ds_read_b128 v[0:3], v193
	s_waitcnt lgkmcnt(0)
	v_mfma_f32_32x32x16_bf16 v[32:47], v[0:3], v[48:51], 0
	ds_read_b128 v[0:3], v193 offset:32
	s_waitcnt lgkmcnt(0)
	v_mfma_f32_32x32x16_bf16 v[32:47], v[0:3], v[154:157], v[32:47]
	ds_read_b128 v[0:3], v193 offset:64
	s_waitcnt lgkmcnt(0)
	v_mfma_f32_32x32x16_bf16 v[32:47], v[0:3], v[116:119], v[32:47]
	ds_read_b128 v[0:3], v193 offset:96
	s_waitcnt lgkmcnt(0)
	v_mfma_f32_32x32x16_bf16 v[32:47], v[0:3], v[158:161], v[32:47]
	ds_read_b128 v[0:3], v194
	s_waitcnt lgkmcnt(0)
	v_mfma_f32_32x32x16_bf16 v[16:31], v[0:3], v[48:51], 0
	ds_read_b128 v[0:3], v194 offset:32
	s_waitcnt lgkmcnt(0)
	v_mfma_f32_32x32x16_bf16 v[16:31], v[0:3], v[154:157], v[16:31]
	ds_read_b128 v[0:3], v194 offset:64
	s_waitcnt lgkmcnt(0)
	v_mfma_f32_32x32x16_bf16 v[16:31], v[0:3], v[116:119], v[16:31]
	ds_read_b128 v[0:3], v194 offset:96
	s_waitcnt lgkmcnt(0)
	v_mfma_f32_32x32x16_bf16 v[16:31], v[0:3], v[158:161], v[16:31]
	ds_read_b128 v[0:3], v195
	s_waitcnt lgkmcnt(0)
	v_mfma_f32_32x32x16_bf16 v[0:15], v[0:3], v[48:51], 0
	v_mfma_f32_32x32x16_bf16 v[0:15], v[52:55], v[154:157], v[0:15]
	ds_read_b128 v[52:55], v195 offset:64
	s_waitcnt lgkmcnt(0)
	v_mfma_f32_32x32x16_bf16 v[0:15], v[52:55], v[116:119], v[0:15]
	ds_read_b128 v[52:55], v195 offset:96
	s_waitcnt lgkmcnt(0)
	v_mfma_f32_32x32x16_bf16 v[0:15], v[52:55], v[158:161], v[0:15]
	ds_read_b128 v[52:55], v196
	s_waitcnt lgkmcnt(0)
	v_mfma_f32_32x32x16_bf16 v[48:63], v[52:55], v[48:51], 0
	v_mfma_f32_32x32x16_bf16 v[48:63], v[162:165], v[154:157], v[48:63]
	ds_read_b128 v[154:157], v196 offset:64
	s_waitcnt lgkmcnt(0)
	v_mfma_f32_32x32x16_bf16 v[48:63], v[154:157], v[116:119], v[48:63]
	ds_read_b128 v[116:119], v196 offset:96
	s_waitcnt lgkmcnt(0)
	v_mfma_f32_32x32x16_bf16 v[48:63], v[116:119], v[158:161], v[48:63]
	s_cbranch_scc0 .LBB0_356
	v_cndmask_b32_e64 v158, v212, v64, s[2:3]
	v_cndmask_b32_e64 v157, v65, v212, s[4:5]
	v_cndmask_b32_e64 v156, v212, v66, s[6:7]
	v_cndmask_b32_e64 v155, v212, v67, s[8:9]
	v_cndmask_b32_e64 v154, v212, v68, s[10:11]
	v_cndmask_b32_e64 v119, v212, v69, s[12:13]
	v_cndmask_b32_e64 v118, v212, v70, s[14:15]
	v_cndmask_b32_e64 v99, v212, v71, s[16:17]
	v_cndmask_b32_e64 v71, v212, v72, s[18:19]
	v_cndmask_b32_e64 v70, v212, v73, s[20:21]
	v_cndmask_b32_e64 v69, v212, v74, s[22:23]
	v_cndmask_b32_e64 v68, v212, v75, s[24:25]
	v_cndmask_b32_e64 v67, v212, v76, s[26:27]
	v_cndmask_b32_e64 v66, v212, v77, s[28:29]
	v_cndmask_b32_e64 v65, v212, v78, s[30:31]
	v_cndmask_b32_e64 v64, v212, v79, s[34:35]
	s_branch .LBB0_357

.LBB0_357:
	s_mov_b32 s64, 0xff800000
	v_cndmask_b32_e64 v72, v48, v212, s[2:3]
	v_cndmask_b32_e64 v216, v72, v48, s[4:5]
	v_max3_f32 v48, v158, s64, v157
	v_max3_f32 v48, v48, v156, v155
	v_max3_f32 v48, v48, v154, v119
	v_max3_f32 v48, v48, v118, v99
	v_max3_f32 v48, v48, v71, v70
	v_max3_f32 v48, v48, v69, v68
	v_max3_f32 v48, v48, v67, v66
	v_max3_f32 v48, v48, v65, v64
	v_max3_f32 v48, v48, v32, v33
	v_max3_f32 v48, v48, v34, v35
	v_max3_f32 v48, v48, v36, v37
	v_max3_f32 v48, v48, v38, v39
	v_max3_f32 v48, v48, v40, v41
	v_max3_f32 v48, v48, v42, v43
	v_max3_f32 v48, v48, v44, v45
	v_max3_f32 v48, v48, v46, v47
	v_max3_f32 v48, v48, v16, v17
	v_max3_f32 v48, v48, v18, v19
	v_max3_f32 v48, v48, v20, v21
	v_max3_f32 v48, v48, v22, v23
	v_max3_f32 v48, v48, v24, v25
	v_max3_f32 v48, v48, v26, v27
	v_max3_f32 v48, v48, v28, v29
	v_max3_f32 v48, v48, v30, v31
	v_max3_f32 v48, v48, v0, v1
	v_max3_f32 v48, v48, v2, v3
	v_max3_f32 v48, v48, v4, v5
	v_max3_f32 v48, v48, v6, v7
	v_max3_f32 v48, v48, v8, v9
	v_max3_f32 v48, v48, v10, v11
	v_max3_f32 v48, v48, v12, v13
	v_cndmask_b32_e64 v215, v212, v49, s[4:5]
	v_max3_f32 v48, v48, v14, v15
	v_cndmask_b32_e64 v217, v50, v212, s[6:7]
	v_cndmask_b32_e64 v218, v51, v212, s[8:9]
	v_max3_f32 v48, v48, v216, v215
	v_cndmask_b32_e64 v219, v52, v212, s[10:11]
	v_cndmask_b32_e64 v220, v53, v212, s[12:13]
	v_max3_f32 v48, v48, v217, v218
	v_cndmask_b32_e64 v221, v54, v212, s[14:15]
	v_cndmask_b32_e64 v222, v55, v212, s[16:17]
	v_max3_f32 v48, v48, v219, v220
	v_cndmask_b32_e64 v223, v56, v212, s[18:19]
	v_cndmask_b32_e64 v224, v57, v212, s[20:21]
	v_max3_f32 v48, v48, v221, v222
	v_cndmask_b32_e64 v225, v58, v212, s[22:23]
	v_cndmask_b32_e64 v226, v59, v212, s[24:25]
	v_max3_f32 v48, v48, v223, v224
	v_cndmask_b32_e64 v227, v60, v212, s[26:27]
	v_cndmask_b32_e64 v228, v61, v212, s[28:29]
	v_max3_f32 v48, v48, v225, v226
	v_cndmask_b32_e64 v229, v62, v212, s[30:31]
	v_cndmask_b32_e64 v230, v63, v212, s[34:35]
	v_max3_f32 v48, v48, v227, v228
	v_max3_f32 v48, v48, v229, v230
	ds_bpermute_b32 v49, v188, v48
	v_mul_f32_e32 v96, 0x3fb8aa3b, v214
	v_or_b32_e32 v213, s89, v98
	s_mov_b32 s55, 0x3fb8aa3b
	s_lshl_b32 s94, s69, 1
	s_waitcnt lgkmcnt(0)
	v_max3_f32 v231, v48, v49, v96
	v_sub_f32_e32 v50, v156, v231
	v_exp_f32_e32 v170, v50
	v_sub_f32_e32 v50, v155, v231
	v_exp_f32_e32 v171, v50
	v_sub_f32_e32 v50, v154, v231
	v_exp_f32_e32 v176, v50
	v_sub_f32_e32 v50, v119, v231
	v_exp_f32_e32 v177, v50
	v_sub_f32_e32 v50, v118, v231
	v_sub_f32_e32 v48, v158, v231
	v_exp_f32_e32 v180, v50
	v_sub_f32_e32 v50, v99, v231
	v_exp_f32_e32 v162, v48
	v_sub_f32_e32 v48, v157, v231
	v_exp_f32_e32 v181, v50
	v_sub_f32_e32 v50, v71, v231
	v_exp_f32_e32 v163, v48
	v_exp_f32_e32 v154, v50
	v_sub_f32_e32 v50, v70, v231
	v_exp_f32_e32 v155, v50
	v_pk_add_f32 v[232:233], v[68:69], v[230:231] op_sel:[0,1] op_sel_hi:[1,1] neg_lo:[0,1] neg_hi:[0,1]
	v_pk_add_f32 v[234:235], v[34:35], v[230:231] op_sel:[0,1] op_sel_hi:[1,1] neg_lo:[0,1] neg_hi:[0,1]
	v_exp_f32_e32 v164, v233
	v_exp_f32_e32 v158, v234
	v_exp_f32_e32 v165, v232
	v_pk_add_f32 v[232:233], v[66:67], v[230:231] op_sel:[0,1] op_sel_hi:[1,1] neg_lo:[0,1] neg_hi:[0,1]
	v_exp_f32_e32 v159, v235
	v_pk_add_f32 v[234:235], v[36:37], v[230:231] op_sel:[0,1] op_sel_hi:[1,1] neg_lo:[0,1] neg_hi:[0,1]
	v_pk_add_f32 v[48:49], v[162:163], 0 op_sel_hi:[1,0]
	v_exp_f32_e32 v172, v233
	v_exp_f32_e32 v166, v234
	v_pk_add_f32 v[48:49], v[170:171], v[48:49]
	v_exp_f32_e32 v173, v232
	v_pk_add_f32 v[232:233], v[64:65], v[230:231] op_sel:[0,1] op_sel_hi:[1,1] neg_lo:[0,1] neg_hi:[0,1]
	v_exp_f32_e32 v167, v235
	v_pk_add_f32 v[234:235], v[38:39], v[230:231] op_sel:[0,1] op_sel_hi:[1,1] neg_lo:[0,1] neg_hi:[0,1]
	v_pk_add_f32 v[48:49], v[176:177], v[48:49]
	v_exp_f32_e32 v178, v233
	v_pk_add_f32 v[236:237], v[32:33], v[230:231] op_sel:[0,1] op_sel_hi:[1,1] neg_lo:[0,1] neg_hi:[0,1]
	v_exp_f32_e32 v174, v234
	v_pk_add_f32 v[48:49], v[180:181], v[48:49]
	v_exp_f32_e32 v179, v232
	v_exp_f32_e32 v78, v236
	v_exp_f32_e32 v175, v235
	v_pk_add_f32 v[232:233], v[40:41], v[230:231] op_sel:[0,1] op_sel_hi:[1,1] neg_lo:[0,1] neg_hi:[0,1]
	v_pk_add_f32 v[48:49], v[154:155], v[48:49]
	v_exp_f32_e32 v79, v237
	v_exp_f32_e32 v70, v232
	v_pk_add_f32 v[48:49], v[164:165], v[48:49]
	v_exp_f32_e32 v71, v233
	v_pk_add_f32 v[232:233], v[42:43], v[230:231] op_sel:[0,1] op_sel_hi:[1,1] neg_lo:[0,1] neg_hi:[0,1]
	v_pk_add_f32 v[234:235], v[18:19], v[230:231] op_sel:[0,1] op_sel_hi:[1,1] neg_lo:[0,1] neg_hi:[0,1]
	v_pk_add_f32 v[236:237], v[2:3], v[230:231] op_sel:[0,1] op_sel_hi:[1,1] neg_lo:[0,1] neg_hi:[0,1]
	v_pk_add_f32 v[48:49], v[172:173], v[48:49]
	v_exp_f32_e32 v76, v232
	v_exp_f32_e32 v74, v234
	v_exp_f32_e32 v60, v236
	v_pk_add_f32 v[48:49], v[178:179], v[48:49]
	v_exp_f32_e32 v77, v233
	v_pk_add_f32 v[232:233], v[44:45], v[230:231] op_sel:[0,1] op_sel_hi:[1,1] neg_lo:[0,1] neg_hi:[0,1]
	v_exp_f32_e32 v75, v235
	v_pk_add_f32 v[234:235], v[20:21], v[230:231] op_sel:[0,1] op_sel_hi:[1,1] neg_lo:[0,1] neg_hi:[0,1]
	v_exp_f32_e32 v61, v237
	v_pk_add_f32 v[236:237], v[4:5], v[230:231] op_sel:[0,1] op_sel_hi:[1,1] neg_lo:[0,1] neg_hi:[0,1]
	v_pk_add_f32 v[32:33], v[78:79], v[48:49]
	v_exp_f32_e32 v156, v232
	v_exp_f32_e32 v98, v234
	v_exp_f32_e32 v66, v236
	v_pk_add_f32 v[32:33], v[158:159], v[32:33]
	v_exp_f32_e32 v157, v233
	v_pk_add_f32 v[232:233], v[46:47], v[230:231] op_sel:[0,1] op_sel_hi:[1,1] neg_lo:[0,1] neg_hi:[0,1]
	v_exp_f32_e32 v99, v235
	v_pk_add_f32 v[234:235], v[22:23], v[230:231] op_sel:[0,1] op_sel_hi:[1,1] neg_lo:[0,1] neg_hi:[0,1]
	v_exp_f32_e32 v67, v237
	v_pk_add_f32 v[236:237], v[6:7], v[230:231] op_sel:[0,1] op_sel_hi:[1,1] neg_lo:[0,1] neg_hi:[0,1]
	v_pk_add_f32 v[32:33], v[166:167], v[32:33]
	v_exp_f32_e32 v168, v232
	v_pk_add_f32 v[238:239], v[16:17], v[230:231] op_sel:[0,1] op_sel_hi:[1,1] neg_lo:[0,1] neg_hi:[0,1]
	v_exp_f32_e32 v160, v234
	v_exp_f32_e32 v68, v236
	v_pk_add_f32 v[32:33], v[174:175], v[32:33]
	v_exp_f32_e32 v169, v233
	v_exp_f32_e32 v64, v238
	v_exp_f32_e32 v161, v235
	v_pk_add_f32 v[232:233], v[24:25], v[230:231] op_sel:[0,1] op_sel_hi:[1,1] neg_lo:[0,1] neg_hi:[0,1]
	v_exp_f32_e32 v69, v237
	v_pk_add_f32 v[234:235], v[8:9], v[230:231] op_sel:[0,1] op_sel_hi:[1,1] neg_lo:[0,1] neg_hi:[0,1]
	v_pk_add_f32 v[32:33], v[70:71], v[32:33]
	v_exp_f32_e32 v65, v239
	v_exp_f32_e32 v58, v232
	v_exp_f32_e32 v48, v234
	v_pk_add_f32 v[32:33], v[76:77], v[32:33]
	v_exp_f32_e32 v59, v233
	v_pk_add_f32 v[232:233], v[26:27], v[230:231] op_sel:[0,1] op_sel_hi:[1,1] neg_lo:[0,1] neg_hi:[0,1]
	v_exp_f32_e32 v49, v235
	v_pk_add_f32 v[234:235], v[10:11], v[230:231] op_sel:[0,1] op_sel_hi:[1,1] neg_lo:[0,1] neg_hi:[0,1]
	v_pk_add_f32 v[32:33], v[156:157], v[32:33]
	v_exp_f32_e32 v62, v232
	v_exp_f32_e32 v50, v234
	v_pk_add_f32 v[32:33], v[168:169], v[32:33]
	v_exp_f32_e32 v63, v233
	v_pk_add_f32 v[232:233], v[28:29], v[230:231] op_sel:[0,1] op_sel_hi:[1,1] neg_lo:[0,1] neg_hi:[0,1]
	v_exp_f32_e32 v51, v235
	v_pk_add_f32 v[234:235], v[12:13], v[230:231] op_sel:[0,1] op_sel_hi:[1,1] neg_lo:[0,1] neg_hi:[0,1]
	v_pk_add_f32 v[16:17], v[64:65], v[32:33]
	v_exp_f32_e32 v72, v232
	v_exp_f32_e32 v52, v234
	v_pk_add_f32 v[16:17], v[74:75], v[16:17]
	v_exp_f32_e32 v73, v233
	v_pk_add_f32 v[232:233], v[30:31], v[230:231] op_sel:[0,1] op_sel_hi:[1,1] neg_lo:[0,1] neg_hi:[0,1]
	v_exp_f32_e32 v53, v235
	v_pk_add_f32 v[234:235], v[14:15], v[230:231] op_sel:[0,1] op_sel_hi:[1,1] neg_lo:[0,1] neg_hi:[0,1]
	v_pk_add_f32 v[16:17], v[98:99], v[16:17]
	v_exp_f32_e32 v118, v232
	v_pk_add_f32 v[236:237], v[0:1], v[230:231] op_sel:[0,1] op_sel_hi:[1,1] neg_lo:[0,1] neg_hi:[0,1]
	v_exp_f32_e32 v54, v234
	v_pk_add_f32 v[16:17], v[160:161], v[16:17]
	v_exp_f32_e32 v119, v233
	v_exp_f32_e32 v56, v236
	v_exp_f32_e32 v55, v235
	v_pk_add_f32 v[232:233], v[216:217], v[230:231] op_sel:[0,1] op_sel_hi:[1,1] neg_lo:[0,1] neg_hi:[0,1]
	v_pk_add_f32 v[16:17], v[58:59], v[16:17]
	v_exp_f32_e32 v57, v237
	v_exp_f32_e32 v40, v232
	v_sub_f32_e32 v2, v215, v231
	v_pk_add_f32 v[16:17], v[62:63], v[16:17]
	v_exp_f32_e32 v41, v2
	v_pk_add_f32 v[16:17], v[72:73], v[16:17]
	v_exp_f32_e32 v42, v233
	v_pk_add_f32 v[232:233], v[218:219], v[230:231] op_sel:[0,1] op_sel_hi:[1,1] neg_lo:[0,1] neg_hi:[0,1]
	v_pk_add_f32 v[16:17], v[118:119], v[16:17]
	v_exp_f32_e32 v43, v232
	v_pk_add_f32 v[0:1], v[56:57], v[16:17]
	v_exp_f32_e32 v44, v233
	v_pk_add_f32 v[232:233], v[220:221], v[230:231] op_sel:[0,1] op_sel_hi:[1,1] neg_lo:[0,1] neg_hi:[0,1]
	v_pk_add_f32 v[0:1], v[60:61], v[0:1]
	v_exp_f32_e32 v45, v232
	v_pk_add_f32 v[0:1], v[66:67], v[0:1]
	v_exp_f32_e32 v46, v233
	v_pk_add_f32 v[232:233], v[222:223], v[230:231] op_sel:[0,1] op_sel_hi:[1,1] neg_lo:[0,1] neg_hi:[0,1]
	v_pk_add_f32 v[0:1], v[68:69], v[0:1]
	v_exp_f32_e32 v47, v232
	v_pk_add_f32 v[0:1], v[48:49], v[0:1]
	v_exp_f32_e32 v32, v233
	v_pk_add_f32 v[232:233], v[224:225], v[230:231] op_sel:[0,1] op_sel_hi:[1,1] neg_lo:[0,1] neg_hi:[0,1]
	v_pk_add_f32 v[0:1], v[50:51], v[0:1]
	v_exp_f32_e32 v33, v232
	v_pk_add_f32 v[0:1], v[52:53], v[0:1]
	v_exp_f32_e32 v34, v233
	v_pk_add_f32 v[232:233], v[226:227], v[230:231] op_sel:[0,1] op_sel_hi:[1,1] neg_lo:[0,1] neg_hi:[0,1]
	v_pk_add_f32 v[0:1], v[54:55], v[0:1]
	v_exp_f32_e32 v35, v232
	v_pk_add_f32 v[0:1], v[40:41], v[0:1]
	v_exp_f32_e32 v36, v233
	v_pk_add_f32 v[232:233], v[228:229], v[230:231] op_sel:[0,1] op_sel_hi:[1,1] neg_lo:[0,1] neg_hi:[0,1]
	v_pk_add_f32 v[0:1], v[42:43], v[0:1]
	v_exp_f32_e32 v37, v232
	v_pk_add_f32 v[0:1], v[44:45], v[0:1]
	v_exp_f32_e32 v38, v233
	v_sub_f32_e32 v2, v230, v231
	v_pk_add_f32 v[0:1], v[46:47], v[0:1]
	v_exp_f32_e32 v39, v2
	v_pk_add_f32 v[0:1], v[32:33], v[0:1]
	v_cvt_pk_bf16_f32 v16, v162, v163
	v_cvt_pk_bf16_f32 v17, v170, v171
	v_add_u32_e32 v170, 0x9000, v197
	v_pk_add_f32 v[0:1], v[34:35], v[0:1]
	v_cvt_pk_bf16_f32 v18, v176, v177
	v_cvt_pk_bf16_f32 v19, v180, v181
	v_add_u32_e32 v176, 0xd000, v197
	v_pk_add_f32 v[0:1], v[36:37], v[0:1]
	ds_read2_b64 v[20:23], v176 offset0:32 offset1:34
	v_pk_add_f32 v[0:1], v[38:39], v[0:1]
	v_lshl_add_u64 v[116:117], v[146:147], 0, s[94:95]
	v_add_f32_e32 v0, v0, v1
	ds_bpermute_b32 v1, v188, v0
	s_mov_b32 s97, s0
	v_readlane_b32 s0, v255, 15
	s_waitcnt lgkmcnt(0)
	v_add_f32_e32 v0, v0, v1
	v_fma_f32 v1, v214, s55, -v231
	v_exp_f32_e32 v1, v1
	s_nop 0
	v_add_f32_e32 v214, v1, v0
	ds_read2_b64 v[0:3], v170 offset1:2
	v_cvt_pk_bf16_f32 v162, v154, v155
	v_cvt_pk_bf16_f32 v163, v164, v165
	v_cvt_pk_bf16_f32 v164, v172, v173
	v_cvt_pk_bf16_f32 v165, v178, v179
	ds_read2_b64 v[170:173], v170 offset0:4 offset1:6
	s_waitcnt lgkmcnt(1)
	v_mfma_f32_32x32x16_bf16 v[0:15], v[0:3], v[16:19], 0
	s_waitcnt lgkmcnt(0)
	v_mfma_f32_32x32x16_bf16 v[0:15], v[170:173], v[162:165], v[0:15]
	ds_read2_b64 v[170:173], v176 offset0:36 offset1:38
	v_mfma_f32_32x32x16_bf16 v[16:31], v[20:23], v[16:19], 0
	s_waitcnt lgkmcnt(0)
	v_mfma_f32_32x32x16_bf16 v[16:31], v[170:173], v[162:165], v[16:31]
	v_cvt_pk_bf16_f32 v162, v78, v79
	v_add_u32_e32 v78, 0x9000, v198
	v_cvt_pk_bf16_f32 v163, v158, v159
	v_cvt_pk_bf16_f32 v164, v166, v167
	v_cvt_pk_bf16_f32 v165, v174, v175
	ds_read2_b64 v[170:173], v78 offset1:2
	v_add_u32_e32 v158, 0xd000, v198
	s_waitcnt lgkmcnt(0)
	v_mfma_f32_32x32x16_bf16 v[0:15], v[170:173], v[162:165], v[0:15]
	ds_read2_b64 v[170:173], v158 offset0:32 offset1:34
	v_cvt_pk_bf16_f32 v154, v70, v71
	v_cvt_pk_bf16_f32 v155, v76, v77
	v_cvt_pk_bf16_f32 v156, v156, v157
	v_cvt_pk_bf16_f32 v157, v168, v169
	ds_read2_b64 v[76:79], v78 offset0:4 offset1:6
	s_waitcnt lgkmcnt(0)
	v_mfma_f32_32x32x16_bf16 v[0:15], v[76:79], v[154:157], v[0:15]
	ds_read2_b64 v[76:79], v158 offset0:36 offset1:38
	v_mfma_f32_32x32x16_bf16 v[16:31], v[170:173], v[162:165], v[16:31]
	s_waitcnt lgkmcnt(0)
	v_mfma_f32_32x32x16_bf16 v[16:31], v[76:79], v[154:157], v[16:31]
	v_cvt_pk_bf16_f32 v76, v64, v65
	v_add_u32_e32 v64, 0x9000, v199
	v_cvt_pk_bf16_f32 v77, v74, v75
	v_cvt_pk_bf16_f32 v78, v98, v99
	v_cvt_pk_bf16_f32 v79, v160, v161
	ds_read2_b64 v[154:157], v64 offset1:2
	v_add_u32_e32 v74, 0xd000, v199
	s_waitcnt lgkmcnt(0)
	v_mfma_f32_32x32x16_bf16 v[0:15], v[154:157], v[76:79], v[0:15]
	ds_read2_b64 v[154:157], v74 offset0:32 offset1:34
	v_cvt_pk_bf16_f32 v70, v58, v59
	v_cvt_pk_bf16_f32 v71, v62, v63
	v_cvt_pk_bf16_f32 v72, v72, v73
	v_cvt_pk_bf16_f32 v73, v118, v119
	ds_read2_b64 v[62:65], v64 offset0:4 offset1:6
	v_or_b32_e32 v118, s0, v153
	s_waitcnt lgkmcnt(0)
	v_mfma_f32_32x32x16_bf16 v[0:15], v[62:65], v[70:73], v[0:15]
	ds_read2_b64 v[62:65], v74 offset0:36 offset1:38
	v_cvt_pk_bf16_f32 v56, v56, v57
	v_cvt_pk_bf16_f32 v57, v60, v61
	v_cvt_pk_bf16_f32 v58, v66, v67
	v_cvt_pk_bf16_f32 v59, v68, v69
	v_and_b32_e32 v67, 0xffff0000, v103
	v_and_b32_e32 v66, 0xffff0000, v107
	v_mfma_f32_32x32x16_bf16 v[16:31], v[154:157], v[76:79], v[16:31]
	v_lshlrev_b32_e32 v155, 16, v100
	v_lshlrev_b32_e32 v154, 16, v104
	v_and_b32_e32 v79, 0xffff0000, v102
	v_and_b32_e32 v78, 0xffff0000, v106
	s_waitcnt lgkmcnt(0)
	v_mfma_f32_32x32x16_bf16 v[16:31], v[62:65], v[70:73], v[16:31]
	v_add_u32_e32 v64, 0x9000, v200
	ds_read2_b64 v[60:63], v64 offset1:2
	v_add_u32_e32 v65, 0xd000, v200
	v_lshlrev_b32_e32 v71, 16, v102
	v_lshlrev_b32_e32 v102, 16, v105
	v_lshlrev_b32_e32 v70, 16, v106
	s_waitcnt lgkmcnt(0)
	v_mfma_f32_32x32x16_bf16 v[0:15], v[60:63], v[56:59], v[0:15]
	ds_read2_b64 v[60:63], v65 offset0:32 offset1:34
	v_cvt_pk_bf16_f32 v48, v48, v49
	v_cvt_pk_bf16_f32 v49, v50, v51
	v_cvt_pk_bf16_f32 v50, v52, v53
	v_cvt_pk_bf16_f32 v51, v54, v55
	ds_read2_b64 v[52:55], v64 offset0:4 offset1:6
	s_waitcnt lgkmcnt(0)
	v_mfma_f32_32x32x16_bf16 v[0:15], v[52:55], v[48:51], v[0:15]
	ds_read2_b64 v[52:55], v65 offset0:36 offset1:38
	v_cvt_pk_bf16_f32 v40, v40, v41
	v_cvt_pk_bf16_f32 v41, v42, v43
	v_cvt_pk_bf16_f32 v42, v44, v45
	v_cvt_pk_bf16_f32 v43, v46, v47
	v_mfma_f32_32x32x16_bf16 v[16:31], v[60:63], v[56:59], v[16:31]
	v_lshlrev_b32_e32 v59, 16, v103
	v_lshlrev_b32_e32 v103, 16, v101
	v_lshlrev_b32_e32 v58, 16, v107
	s_waitcnt lgkmcnt(0)
	v_mfma_f32_32x32x16_bf16 v[16:31], v[52:55], v[48:51], v[16:31]
	v_add_u32_e32 v48, 0x9000, v201
	ds_read2_b64 v[44:47], v48 offset1:2
	v_add_u32_e32 v49, 0xd000, v201
	s_waitcnt lgkmcnt(0)
	v_mfma_f32_32x32x16_bf16 v[0:15], v[44:47], v[40:43], v[0:15]
	ds_read2_b64 v[44:47], v49 offset0:32 offset1:34
	v_cvt_pk_bf16_f32 v32, v32, v33
	v_cvt_pk_bf16_f32 v33, v34, v35
	v_cvt_pk_bf16_f32 v34, v36, v37
	v_cvt_pk_bf16_f32 v35, v38, v39
	ds_read2_b64 v[36:39], v48 offset0:4 offset1:6
	s_waitcnt lgkmcnt(0)
	v_mfma_f32_32x32x16_bf16 v[0:15], v[36:39], v[32:35], v[0:15]
	ds_read2_b64 v[36:39], v49 offset0:36 offset1:38
	v_mfma_f32_32x32x16_bf16 v[16:31], v[44:47], v[40:43], v[16:31]
	v_lshlrev_b32_e32 v42, 16, v112
	v_lshlrev_b32_e32 v43, 16, v108
	s_waitcnt lgkmcnt(0)
	v_mfma_f32_32x32x16_bf16 v[16:31], v[36:39], v[32:35], v[16:31]
	v_div_scale_f32 v32, s[68:69], v214, v214, 1.0
	v_rcp_f32_e32 v33, v32
	v_lshlrev_b32_e32 v38, 16, v113
	v_lshlrev_b32_e32 v39, 16, v109
	v_fma_f32 v34, -v32, v33, 1.0
	v_fmac_f32_e32 v33, v34, v33
	v_div_scale_f32 v34, vcc, 1.0, v214, 1.0
	v_mul_f32_e32 v35, v34, v33
	v_fma_f32 v36, -v32, v35, v34
	v_fmac_f32_e32 v35, v36, v33
	v_fma_f32 v32, -v32, v35, v34
	v_div_fmas_f32 v32, v32, v33, v35
	v_div_fixup_f32 v34, v32, v214, 1.0
	v_mul_f32_e32 v0, v0, v34
	v_mul_f32_e32 v1, v1, v34
	v_cvt_pk_bf16_f32 v0, v0, v1
	v_mul_f32_e32 v1, v2, v34
	v_mad_i64_i32 v[32:33], s[68:69], v213, s65, v[116:117]
	v_and_b32_e32 v36, 63, v251
	v_and_b32_e32 v35, 31, v251
	v_lshrrev_b32_e32 v37, 5, v36
	v_lshlrev_b32_e32 v37, 3, v37
	s_movk_i32 s58, 0x90
	v_mad_u32_u24 v35, v35, s58, v37
	s_movk_i32 s59, 0x1200
	v_mad_u32_u24 v35, v254, s59, v35
	v_add_u32_e32 v35, 0x12000, v35
	v_lshrrev_b32_e32 v37, 3, v36
	v_and_b32_e32 v40, 7, v36
	v_lshlrev_b32_e32 v40, 4, v40
	v_mad_u32_u24 v36, v37, s58, v40
	v_mad_u32_u24 v36, v254, s59, v36
	v_add_u32_e32 v36, 0x12000, v36
	s_movk_i32 s58, 0xc00
	v_mad_u32_u24 v37, v37, s58, v40
	v_readfirstlane_b32 s56, v32
	v_readfirstlane_b32 s57, v33
	v_mul_f32_e32 v2, v3, v34
	v_cvt_pk_bf16_f32 v1, v1, v2
	ds_write_b64 v35, v[0:1]
	v_mul_f32_e32 v0, v4, v34
	v_mul_f32_e32 v1, v5, v34
	v_cvt_pk_bf16_f32 v0, v0, v1
	v_mul_f32_e32 v1, v6, v34
	v_mul_f32_e32 v2, v7, v34
	v_cvt_pk_bf16_f32 v1, v1, v2
	ds_write_b64 v35, v[0:1] offset:16
	v_mul_f32_e32 v0, v8, v34
	v_mul_f32_e32 v1, v9, v34
	v_cvt_pk_bf16_f32 v0, v0, v1
	v_mul_f32_e32 v1, v10, v34
	v_mul_f32_e32 v2, v11, v34
	v_cvt_pk_bf16_f32 v1, v1, v2
	ds_write_b64 v35, v[0:1] offset:32
	v_mul_f32_e32 v0, v12, v34
	v_mul_f32_e32 v1, v13, v34
	v_cvt_pk_bf16_f32 v0, v0, v1
	v_mul_f32_e32 v1, v14, v34
	v_mul_f32_e32 v2, v15, v34
	v_cvt_pk_bf16_f32 v1, v1, v2
	ds_write_b64 v35, v[0:1] offset:48
	v_mul_f32_e32 v0, v16, v34
	v_mul_f32_e32 v1, v17, v34
	v_cvt_pk_bf16_f32 v0, v0, v1
	v_mul_f32_e32 v1, v18, v34
	v_mul_f32_e32 v2, v19, v34
	v_cvt_pk_bf16_f32 v1, v1, v2
	ds_write_b64 v35, v[0:1] offset:64
	v_mul_f32_e32 v0, v20, v34
	v_mul_f32_e32 v1, v21, v34
	v_cvt_pk_bf16_f32 v0, v0, v1
	v_mul_f32_e32 v1, v22, v34
	v_mul_f32_e32 v2, v23, v34
	v_cvt_pk_bf16_f32 v1, v1, v2
	ds_write_b64 v35, v[0:1] offset:80
	v_mul_f32_e32 v0, v24, v34
	v_mul_f32_e32 v1, v25, v34
	v_cvt_pk_bf16_f32 v0, v0, v1
	v_mul_f32_e32 v1, v26, v34
	v_mul_f32_e32 v2, v27, v34
	v_cvt_pk_bf16_f32 v1, v1, v2
	ds_write_b64 v35, v[0:1] offset:96
	v_mul_f32_e32 v0, v28, v34
	v_mul_f32_e32 v1, v29, v34
	v_cvt_pk_bf16_f32 v0, v0, v1
	v_mul_f32_e32 v1, v30, v34
	v_mul_f32_e32 v2, v31, v34
	v_cvt_pk_bf16_f32 v1, v1, v2
	ds_write_b64 v35, v[0:1] offset:112
	s_waitcnt lgkmcnt(0)
	ds_read_b128 v[0:3], v36
	ds_read_b128 v[4:7], v36 offset:1152
	ds_read_b128 v[8:11], v36 offset:2304
	ds_read_b128 v[12:15], v36 offset:3456
	s_waitcnt lgkmcnt(3)
	global_store_dwordx4 v37, v[0:3], s[56:57]
	s_add_u32 s56, s56, 0x6000
	s_addc_u32 s57, s57, 0
	s_waitcnt lgkmcnt(2)
	global_store_dwordx4 v37, v[4:7], s[56:57]
	s_add_u32 s56, s56, 0x6000
	s_addc_u32 s57, s57, 0
	s_waitcnt lgkmcnt(1)
	global_store_dwordx4 v37, v[8:11], s[56:57]
	s_add_u32 s56, s56, 0x6000
	s_addc_u32 s57, s57, 0
	s_waitcnt lgkmcnt(0)
	global_store_dwordx4 v37, v[12:15], s[56:57]
	s_nop 1
	s_and_b64 vcc, exec, s[76:77]
	s_cbranch_vccnz .Lvpf_skip
	s_lshl_b32 s58, s33, 5
	s_and_b32 s58, s58, 0x780
	s_addk_i32 s58, 0xff80
	v_add_u32_e32 v16, s58, v183
	v_cmp_lt_i32_e32 vcc, -1, v16
	v_mov_b32_e32 v122, 0
	v_mov_b32_e32 v123, 0
	v_mov_b32_e32 v124, 0
	v_mov_b32_e32 v125, 0
	v_mov_b32_e32 v128, 0
	v_mov_b32_e32 v129, 0
	v_mov_b32_e32 v130, 0
	v_mov_b32_e32 v131, 0
	v_mov_b32_e32 v132, 0
	v_mov_b32_e32 v133, 0
	v_mov_b32_e32 v134, 0
	v_mov_b32_e32 v135, 0
	v_mov_b32_e32 v136, 0
	v_mov_b32_e32 v137, 0
	v_mov_b32_e32 v138, 0
	v_mov_b32_e32 v139, 0
	s_and_saveexec_b64 s[80:81], vcc
	s_cbranch_execz .Lvpf_join
	v_readlane_b32 vcc_lo, v255, 6
	v_readlane_b32 vcc_hi, v255, 7
	s_ashr_i32 s59, s33, 6
	v_add_u32_e32 v18, s58, v250
	v_lshl_add_u32 v18, s59, 11, v18
	s_and_b32 s58, s33, 3
	s_lshl_b32 s58, s58, 7
	s_mov_b32 s59, 0
	v_mov_b64_e32 v[16:17], vcc
	v_mad_i64_i32 v[16:17], vcc, v18, s65, v[16:17]
	v_lshl_add_u64 v[16:17], v[16:17], 0, s[58:59]
	v_lshl_add_u64 v[16:17], v[16:17], 0, v[248:249]
	s_movk_i32 s58, 0x6000
	global_load_dwordx4 v[122:125], v[16:17], off offset:2560
	v_lshl_add_u64 v[16:17], v[16:17], 0, s[58:59]
	global_load_dwordx4 v[128:131], v[16:17], off offset:2560
	v_lshl_add_u64 v[16:17], v[16:17], 0, s[58:59]
	global_load_dwordx4 v[132:135], v[16:17], off offset:2560
	v_lshl_add_u64 v[16:17], v[16:17], 0, s[58:59]
	global_load_dwordx4 v[136:139], v[16:17], off offset:2560

.Lvpf_skip:
	ds_read_b128 v[0:3], v243 offset:16
	s_nop 0
	ds_read_b128 v[16:19], v243
	ds_read_b128 v[4:7], v243 offset:144
	ds_read_b128 v[20:23], v243 offset:128
	v_lshlrev_b32_e32 v28, 5, v118
	v_or_b32_e32 v8, v28, v126
	v_lshlrev_b32_e32 v29, 2, v8
	ds_read_b128 v[8:11], v252 offset:6144
	ds_read_b128 v[24:27], v252 offset:2048
	ds_read_b128 v[12:15], v252 offset:24192
	ds_read_b128 v[44:47], v252 offset:20096
	v_or_b32_e32 v28, v28, v127
	v_lshlrev_b32_e32 v119, 2, v28
	v_lshlrev_b32_e32 v30, 16, v115
	v_and_b32_e32 v28, 0xffff0000, v115
	v_lshlrev_b32_e32 v34, 16, v114
	v_and_b32_e32 v32, 0xffff0000, v114
	v_and_b32_e32 v36, 0xffff0000, v113
	v_and_b32_e32 v113, 0xffff0000, v101
	v_and_b32_e32 v101, 0xffff0000, v100
	v_and_b32_e32 v100, 0xffff0000, v104
	v_and_b32_e32 v40, 0xffff0000, v112
	v_and_b32_e32 v112, 0xffff0000, v105
	v_and_b32_e32 v41, 0xffff0000, v108
	v_and_b32_e32 v37, 0xffff0000, v109
	v_lshlrev_b32_e32 v35, 16, v110
	v_and_b32_e32 v33, 0xffff0000, v110
	v_lshlrev_b32_e32 v31, 16, v111
	v_and_b32_e32 v29, 0xffff0000, v111
	s_andn2_b64 vcc, exec, s[78:79]
	s_waitcnt lgkmcnt(0)
	v_mov_b32_e32 v75, v0
	v_mov_b32_e32 v63, v2
	v_pk_mul_f32 v[236:237], v[28:29], v[28:29]
	v_pk_mul_f32 v[238:239], v[30:31], v[30:31]
	v_pk_fma_f32 v[236:237], v[32:33], v[32:33], v[236:237]
	v_pk_fma_f32 v[238:239], v[34:35], v[34:35], v[238:239]
	v_pk_fma_f32 v[236:237], v[36:37], v[36:37], v[236:237]
	v_pk_fma_f32 v[238:239], v[38:39], v[38:39], v[238:239]
	v_pk_fma_f32 v[236:237], v[40:41], v[40:41], v[236:237]
	v_pk_fma_f32 v[238:239], v[42:43], v[42:43], v[238:239]
	v_pk_fma_f32 v[236:237], v[58:59], v[58:59], v[236:237]
	v_pk_fma_f32 v[238:239], v[66:67], v[66:67], v[238:239]
	v_pk_fma_f32 v[236:237], v[70:71], v[70:71], v[236:237]
	v_pk_fma_f32 v[238:239], v[78:79], v[78:79], v[238:239]
	v_pk_fma_f32 v[236:237], v[100:101], v[100:101], v[236:237]
	v_pk_fma_f32 v[238:239], v[102:103], v[102:103], v[238:239]
	v_pk_fma_f32 v[236:237], v[112:113], v[112:113], v[236:237]
	v_pk_fma_f32 v[238:239], v[154:155], v[154:155], v[238:239]
	v_pk_add_f32 v[236:237], v[236:237], v[238:239]
	v_add_f32_e32 v0, v236, v237
	ds_bpermute_b32 v2, v188, v0
	s_waitcnt lgkmcnt(0)
	v_mov_b32_e32 v74, v4
	s_waitcnt lgkmcnt(0)
	v_mov_b32_e32 v158, v20
	s_waitcnt lgkmcnt(0)
	v_mov_b32_e32 v159, v16
	v_mov_b32_e32 v160, v24
	s_waitcnt lgkmcnt(0)
	v_add_f32_e32 v0, v0, v2
	v_fmamk_f32 v0, v0, 0x3c800000, v189
	v_rsq_f32_e32 v0, v0
	v_mov_b32_e32 v161, v44
	v_mov_b32_e32 v50, v44
	v_mov_b32_e32 v51, v24
	v_mul_f32_e32 v4, 0x3e38aa3b, v0
	v_pk_mul_f32 v[48:49], v[4:5], v[154:155] op_sel_hi:[0,1]
	v_pk_mul_f32 v[48:49], v[158:159], v[48:49]
	v_mov_b32_e32 v108, v22
	v_pk_mul_f32 v[50:51], v[50:51], v[48:49]
	v_pk_mul_f32 v[48:49], v[160:161], v[48:49]
	v_mov_b32_e32 v16, v21
	v_add_f32_e32 v22, v48, v49
	v_pk_mul_f32 v[48:49], v[4:5], v[100:101] op_sel_hi:[0,1]
	v_pk_mul_f32 v[16:17], v[16:17], v[48:49]
	v_mov_b32_e32 v24, v45
	v_mov_b32_e32 v44, v25
	v_pk_mul_f32 v[20:21], v[24:25], v[16:17]
	v_pk_mul_f32 v[16:17], v[44:45], v[16:17]
	v_mov_b32_e32 v109, v18
	v_add_f32_e32 v25, v16, v17
	v_pk_mul_f32 v[16:17], v[4:5], v[102:103] op_sel_hi:[0,1]
	v_mov_b32_e32 v110, v26
	v_mov_b32_e32 v111, v46
	v_sub_f32_e32 v24, v21, v20
	v_pk_mul_f32 v[16:17], v[16:17], v[108:109]
	v_mov_b32_e32 v20, v46
	v_mov_b32_e32 v21, v26
	v_pk_mul_f32 v[20:21], v[16:17], v[20:21]
	v_pk_mul_f32 v[16:17], v[16:17], v[110:111]
	v_sub_f32_e32 v20, v21, v20
	v_add_f32_e32 v21, v16, v17
	v_pk_mul_f32 v[16:17], v[4:5], v[112:113] op_sel_hi:[0,1]
	v_mov_b32_e32 v18, v23
	v_pk_mul_f32 v[16:17], v[16:17], v[18:19]
	v_mov_b32_e32 v26, v47
	v_mov_b32_e32 v46, v27
	v_pk_mul_f32 v[18:19], v[16:17], v[26:27]
	v_pk_mul_f32 v[16:17], v[16:17], v[46:47]
	v_mov_b32_e32 v76, v8
	v_add_f32_e32 v26, v16, v17
	v_pk_mul_f32 v[16:17], v[4:5], v[70:71] op_sel_hi:[0,1]
	v_mov_b32_e32 v77, v12
	v_sub_f32_e32 v23, v19, v18
	v_pk_mul_f32 v[16:17], v[16:17], v[74:75]
	v_mov_b32_e32 v18, v12
	v_mov_b32_e32 v19, v8
	v_pk_mul_f32 v[18:19], v[16:17], v[18:19]
	v_pk_mul_f32 v[16:17], v[16:17], v[76:77]
	v_sub_f32_e32 v18, v19, v18
	v_add_f32_e32 v19, v16, v17
	v_pk_mul_f32 v[16:17], v[4:5], v[78:79] op_sel_hi:[0,1]
	v_mov_b32_e32 v0, v5
	v_pk_mul_f32 v[0:1], v[16:17], v[0:1]
	v_mov_b32_e32 v8, v13
	v_pk_mul_f32 v[16:17], v[0:1], v[8:9]
	v_mov_b32_e32 v12, v9
	v_sub_f32_e32 v5, v17, v16
	v_pk_mul_f32 v[0:1], v[0:1], v[12:13]
	v_mov_b32_e32 v62, v6
	v_add_f32_e32 v12, v0, v1
	v_pk_mul_f32 v[0:1], v[4:5], v[58:59] op_sel_hi:[0,1]
	v_mov_b32_e32 v64, v10
	v_mov_b32_e32 v65, v14
	v_pk_mul_f32 v[0:1], v[0:1], v[62:63]
	v_mov_b32_e32 v8, v14
	v_mov_b32_e32 v9, v10
	v_pk_mul_f32 v[8:9], v[0:1], v[8:9]
	v_pk_mul_f32 v[0:1], v[0:1], v[64:65]
	v_sub_f32_e32 v8, v9, v8
	v_add_f32_e32 v9, v0, v1
	v_pk_mul_f32 v[0:1], v[4:5], v[66:67] op_sel_hi:[0,1]
	v_mov_b32_e32 v2, v7
	v_pk_mul_f32 v[0:1], v[0:1], v[2:3]
	v_mov_b32_e32 v10, v15
	v_mov_b32_e32 v14, v11
	v_pk_mul_f32 v[2:3], v[0:1], v[10:11]
	v_pk_mul_f32 v[0:1], v[0:1], v[14:15]
	v_sub_f32_e32 v6, v51, v50
	v_sub_f32_e32 v2, v3, v2
	v_add_f32_e32 v0, v0, v1
	v_cvt_pk_bf16_f32 v48, v6, v24
	v_cvt_pk_bf16_f32 v49, v20, v23
	v_cvt_pk_bf16_f32 v50, v18, v5
	v_cvt_pk_bf16_f32 v51, v8, v2
	v_cvt_pk_bf16_f32 v98, v22, v25
	v_cvt_pk_bf16_f32 v99, v21, v26
	v_cvt_pk_bf16_f32 v100, v19, v12
	v_cvt_pk_bf16_f32 v101, v9, v0
	ds_read_b128 v[0:3], v243 offset:80
	ds_read_b128 v[6:9], v243 offset:64
	ds_read_b128 v[10:13], v243 offset:208
	ds_read_b128 v[14:17], v243 offset:192
	v_pk_mul_f32 v[18:19], v[4:5], v[42:43] op_sel_hi:[0,1]
	s_waitcnt lgkmcnt(0)
	v_mov_b32_e32 v21, v6
	s_waitcnt lgkmcnt(0)
	v_mov_b32_e32 v20, v14
	v_pk_mul_f32 v[26:27], v[18:19], v[20:21]
	ds_read_b128 v[18:21], v252 offset:14336
	ds_read_b128 v[22:25], v252 offset:10240
	ds_read_b128 v[42:45], v252 offset:32384
	ds_read_b128 v[52:55], v252 offset:28288
	v_mov_b32_e32 v6, v15
	s_waitcnt lgkmcnt(0)
	v_mov_b32_e32 v47, v22
	s_waitcnt lgkmcnt(0)
	v_mov_b32_e32 v46, v52
	v_pk_mul_f32 v[46:47], v[26:27], v[46:47]
	s_nop 0
	v_sub_f32_e32 v5, v47, v46
	v_mov_b32_e32 v46, v22
	v_mov_b32_e32 v47, v52
	v_pk_mul_f32 v[26:27], v[26:27], v[46:47]
	v_mov_b32_e32 v22, v53
	v_add_f32_e32 v46, v26, v27
	v_pk_mul_f32 v[26:27], v[4:5], v[40:41] op_sel_hi:[0,1]
	v_pk_mul_f32 v[6:7], v[26:27], v[6:7]
	v_mov_b32_e32 v52, v23
	v_pk_mul_f32 v[14:15], v[6:7], v[22:23]
	v_pk_mul_f32 v[6:7], v[6:7], v[52:53]
	v_sub_f32_e32 v22, v15, v14
	v_add_f32_e32 v23, v6, v7
	v_pk_mul_f32 v[6:7], v[4:5], v[38:39] op_sel_hi:[0,1]
	v_mov_b32_e32 v14, v16
	v_mov_b32_e32 v15, v8
	v_pk_mul_f32 v[6:7], v[6:7], v[14:15]
	v_mov_b32_e32 v14, v54
	v_mov_b32_e32 v15, v24
	v_pk_mul_f32 v[14:15], v[6:7], v[14:15]
	v_mov_b32_e32 v8, v17
	v_sub_f32_e32 v16, v15, v14
	v_mov_b32_e32 v14, v24
	v_mov_b32_e32 v15, v54
	v_pk_mul_f32 v[6:7], v[6:7], v[14:15]
	v_mov_b32_e32 v24, v55
	v_add_f32_e32 v14, v6, v7
	v_pk_mul_f32 v[6:7], v[4:5], v[36:37] op_sel_hi:[0,1]
	v_pk_mul_f32 v[6:7], v[6:7], v[8:9]
	v_mov_b32_e32 v54, v25
	v_pk_mul_f32 v[8:9], v[6:7], v[24:25]
	v_pk_mul_f32 v[6:7], v[6:7], v[54:55]
	v_sub_f32_e32 v15, v9, v8
	v_add_f32_e32 v17, v6, v7
	v_pk_mul_f32 v[6:7], v[4:5], v[34:35] op_sel_hi:[0,1]
	s_waitcnt lgkmcnt(0)
	v_mov_b32_e32 v8, v10
	s_waitcnt lgkmcnt(0)
	v_mov_b32_e32 v9, v0
	v_pk_mul_f32 v[6:7], v[6:7], v[8:9]
	v_mov_b32_e32 v8, v42
	v_mov_b32_e32 v9, v18
	v_pk_mul_f32 v[8:9], v[6:7], v[8:9]
	v_mov_b32_e32 v0, v11
	v_sub_f32_e32 v10, v9, v8
	v_mov_b32_e32 v8, v18
	v_mov_b32_e32 v9, v42
	v_pk_mul_f32 v[6:7], v[6:7], v[8:9]
	v_mov_b32_e32 v18, v43
	v_add_f32_e32 v8, v6, v7
	v_pk_mul_f32 v[6:7], v[4:5], v[32:33] op_sel_hi:[0,1]
	v_pk_mul_f32 v[0:1], v[6:7], v[0:1]
	v_mov_b32_e32 v42, v19
	v_pk_mul_f32 v[6:7], v[0:1], v[18:19]
	v_pk_mul_f32 v[0:1], v[0:1], v[42:43]
	v_sub_f32_e32 v9, v7, v6
	v_add_f32_e32 v11, v0, v1
	v_pk_mul_f32 v[0:1], v[4:5], v[30:31] op_sel_hi:[0,1]
	v_mov_b32_e32 v6, v12
	v_mov_b32_e32 v7, v2
	v_pk_mul_f32 v[0:1], v[0:1], v[6:7]
	v_mov_b32_e32 v6, v44
	v_mov_b32_e32 v7, v20
	v_pk_mul_f32 v[6:7], v[0:1], v[6:7]
	v_mov_b32_e32 v2, v13
	v_sub_f32_e32 v12, v7, v6
	v_mov_b32_e32 v6, v20
	v_mov_b32_e32 v7, v44
	v_pk_mul_f32 v[0:1], v[0:1], v[6:7]
	v_mov_b32_e32 v20, v45
	v_add_f32_e32 v6, v0, v1
	v_pk_mul_f32 v[0:1], v[4:5], v[28:29] op_sel_hi:[0,1]
	v_pk_mul_f32 v[0:1], v[0:1], v[2:3]
	v_mov_b32_e32 v44, v21
	v_pk_mul_f32 v[2:3], v[0:1], v[20:21]
	v_pk_mul_f32 v[0:1], v[0:1], v[44:45]
	v_sub_f32_e32 v2, v3, v2
	v_add_f32_e32 v0, v0, v1
	v_cvt_pk_bf16_f32 v102, v5, v22
	v_cvt_pk_bf16_f32 v103, v16, v15
	v_cvt_pk_bf16_f32 v104, v10, v9
	v_cvt_pk_bf16_f32 v105, v12, v2
	v_cvt_pk_bf16_f32 v106, v46, v23
	v_cvt_pk_bf16_f32 v107, v14, v17
	v_cvt_pk_bf16_f32 v108, v8, v11
	v_cvt_pk_bf16_f32 v109, v6, v0
	ds_read_b128 v[0:3], v202
	ds_read_b128 v[4:7], v202 offset:32
	s_waitcnt lgkmcnt(1)
	v_mfma_f32_32x32x16_bf16 v[64:79], v[0:3], v[48:51], 0
	ds_read_b128 v[0:3], v202 offset:64
	s_waitcnt lgkmcnt(1)
	v_mfma_f32_32x32x16_bf16 v[64:79], v[4:7], v[102:105], v[64:79]
	s_waitcnt lgkmcnt(0)
	v_mfma_f32_32x32x16_bf16 v[64:79], v[0:3], v[98:101], v[64:79]
	ds_read_b128 v[0:3], v202 offset:96
	s_waitcnt lgkmcnt(0)
	v_mfma_f32_32x32x16_bf16 v[64:79], v[0:3], v[106:109], v[64:79]
	ds_read_b128 v[0:3], v203
	ds_read_b128 v[4:7], v203 offset:32
	s_waitcnt lgkmcnt(1)
	v_mfma_f32_32x32x16_bf16 v[32:47], v[0:3], v[48:51], 0
	ds_read_b128 v[0:3], v203 offset:64
	s_waitcnt lgkmcnt(1)
	v_mfma_f32_32x32x16_bf16 v[32:47], v[4:7], v[102:105], v[32:47]
	s_waitcnt lgkmcnt(0)
	v_mfma_f32_32x32x16_bf16 v[32:47], v[0:3], v[98:101], v[32:47]
	ds_read_b128 v[0:3], v203 offset:96
	s_waitcnt lgkmcnt(0)
	v_mfma_f32_32x32x16_bf16 v[32:47], v[0:3], v[106:109], v[32:47]
	ds_read_b128 v[0:3], v204
	ds_read_b128 v[4:7], v204 offset:32
	s_waitcnt lgkmcnt(1)
	v_mfma_f32_32x32x16_bf16 v[16:31], v[0:3], v[48:51], 0
	ds_read_b128 v[0:3], v204 offset:64
	s_waitcnt lgkmcnt(1)
	v_mfma_f32_32x32x16_bf16 v[16:31], v[4:7], v[102:105], v[16:31]
	s_waitcnt lgkmcnt(0)
	v_mfma_f32_32x32x16_bf16 v[16:31], v[0:3], v[98:101], v[16:31]
	ds_read_b128 v[0:3], v204 offset:96
	s_waitcnt lgkmcnt(0)
	v_mfma_f32_32x32x16_bf16 v[16:31], v[0:3], v[106:109], v[16:31]
	ds_read_b128 v[0:3], v205
	ds_read_b128 v[52:55], v205 offset:32
	s_waitcnt lgkmcnt(1)
	v_mfma_f32_32x32x16_bf16 v[0:15], v[0:3], v[48:51], 0
	s_waitcnt lgkmcnt(0)
	v_mfma_f32_32x32x16_bf16 v[0:15], v[52:55], v[102:105], v[0:15]
	ds_read_b128 v[52:55], v205 offset:64
	s_waitcnt lgkmcnt(0)
	v_mfma_f32_32x32x16_bf16 v[0:15], v[52:55], v[98:101], v[0:15]
	ds_read_b128 v[52:55], v205 offset:96
	s_waitcnt lgkmcnt(0)
	v_mfma_f32_32x32x16_bf16 v[0:15], v[52:55], v[106:109], v[0:15]
	ds_read_b128 v[52:55], v206
	ds_read_b128 v[110:113], v206 offset:32
	s_waitcnt lgkmcnt(1)
	v_mfma_f32_32x32x16_bf16 v[48:63], v[52:55], v[48:51], 0
	s_waitcnt lgkmcnt(0)
	v_mfma_f32_32x32x16_bf16 v[48:63], v[110:113], v[102:105], v[48:63]
	ds_read_b128 v[102:105], v206 offset:64
	s_waitcnt lgkmcnt(0)
	v_mfma_f32_32x32x16_bf16 v[48:63], v[102:105], v[98:101], v[48:63]
	ds_read_b128 v[98:101], v206 offset:96
	s_waitcnt lgkmcnt(0)
	v_mfma_f32_32x32x16_bf16 v[48:63], v[98:101], v[106:109], v[48:63]
	s_cbranch_vccz .LBB0_346
	v_cndmask_b32_e64 v98, v212, v64, s[2:3]
	v_cndmask_b32_e64 v105, v65, v212, s[4:5]
	v_cndmask_b32_e64 v104, v212, v66, s[6:7]
	v_cndmask_b32_e64 v103, v212, v67, s[8:9]
	v_cndmask_b32_e64 v102, v212, v68, s[10:11]
	v_cndmask_b32_e64 v101, v212, v69, s[12:13]
	v_cndmask_b32_e64 v100, v212, v70, s[14:15]
	v_cndmask_b32_e64 v99, v212, v71, s[16:17]
	v_cndmask_b32_e64 v71, v212, v72, s[18:19]
	v_cndmask_b32_e64 v70, v212, v73, s[20:21]
	v_cndmask_b32_e64 v69, v212, v74, s[22:23]
	v_cndmask_b32_e64 v68, v212, v75, s[24:25]
	v_cndmask_b32_e64 v67, v212, v76, s[26:27]
	v_cndmask_b32_e64 v66, v212, v77, s[28:29]
	v_cndmask_b32_e64 v65, v212, v78, s[30:31]
	v_cndmask_b32_e64 v64, v212, v79, s[34:35]
	s_branch .LBB0_347
